# prompt attention: static s_setprio 1 for waves 4-7 (on top of hand-scheduled tile step)
# speedup vs baseline: 1.0043x; 1.0043x over previous
.LBB0_73:
	v_readlane_b32 s0, v247, 23
	v_readlane_b32 s1, v247, 24
	s_and_b64 vcc, exec, s[0:1]
	s_cbranch_vccz .LBB0_101
	s_waitcnt vmcnt(0)
	v_ashrrev_i32_e32 v2, 3, v222
	v_ashrrev_i32_e32 v3, 31, v2
	v_and_b32_e32 v5, 64, v191
	v_lshlrev_b64 v[146:147], 13, v[2:3]
	v_xor_b32_e32 v3, 32, v191
	v_add_u32_e32 v5, 64, v5
	s_movk_i32 s0, 0xc0
	v_lshlrev_b32_e32 v4, 3, v222
	v_cmp_lt_i32_e32 vcc, v3, v5
	v_cmp_gt_i32_e64 s[4:5], s0, v222
	v_ashrrev_i32_e32 v168, 4, v222
	v_and_b32_e32 v0, 0x78, v4
	s_mov_b64 s[0:1], 0x80000
	v_cndmask_b32_e32 v3, v191, v3, vcc
	v_and_b32_e32 v4, 56, v4
	v_lshl_add_u64 v[150:151], v[146:147], 0, s[0:1]
	v_lshlrev_b32_e32 v170, 2, v3
	s_movk_i32 s0, 0x90
	v_mul_lo_u32 v3, v168, s97
	v_lshlrev_b32_e32 v5, 1, v0
	s_add_u32 s2, s16, 0x20900000
	v_add3_u32 v173, 0, v3, v5
	v_mul_lo_u32 v2, v2, s0
	v_lshlrev_b32_e32 v3, 1, v4
	v_lshl_add_u32 v176, v155, 4, 0
	s_addc_u32 s3, s17, 0
	s_lshl_b32 s6, s62, 5
	v_add3_u32 v174, 0, v2, v3
	v_sub_u32_e32 v177, v176, v154
	s_ashr_i32 s18, s56, 7
	v_lshlrev_b32_e32 v167, 4, v222
	v_and_or_b32 v169, s6, 32, v149
	v_mul_u32_u24_e32 v171, 0x90, v149
	v_mad_u32_u24 v172, v149, s0, v220
	v_add_u32_e32 v175, 0x2400, v174
	v_mad_u32_u24 v180, v149, s0, v177
	v_add_u32_e32 v181, 0xc0, v168
	v_lshlrev_b32_e32 v0, 1, v0
	v_lshlrev_b32_e32 v152, 1, v4
	v_lshlrev_b32_e32 v154, 1, v154
	v_lshlrev_b32_e32 v156, 1, v148
	v_readlane_b32 s19, v247, 22
	s_cmp_lt_u32 s62, 4
	s_cbranch_scc1 .Lpa_noprio
	s_setprio 1
.Lpa_noprio:
	s_branch .LBB0_76
.LBB0_75:
	ds_bpermute_b32 v68, v170, v153
	v_lshl_add_u64 v[66:67], v[158:159], 1, s[48:49]
	s_lshl_b32 s88, s20, 1
	v_lshl_add_u64 v[66:67], v[66:67], 0, s[88:89]
	v_mov_b32_e32 v157, v1
	s_waitcnt lgkmcnt(0)
	v_add_f32_e32 v68, v153, v68
	v_div_scale_f32 v69, s[0:1], v68, v68, 1.0
	v_rcp_f32_e32 v70, v69
	v_div_scale_f32 v71, vcc, 1.0, v68, 1.0
	v_lshl_add_u64 v[66:67], v[66:67], 0, v[156:157]
	v_fma_f32 v72, -v69, v70, 1.0
	v_fmac_f32_e32 v70, v72, v70
	v_mul_f32_e32 v72, v71, v70
	v_fma_f32 v73, -v69, v72, v71
	v_fmac_f32_e32 v72, v73, v70
	v_fma_f32 v69, -v69, v72, v71
	v_div_fmas_f32 v69, v69, v70, v72
	v_div_fixup_f32 v68, v69, v68, 1.0
	v_pk_mul_f32 v[50:51], v[50:51], v[68:69] op_sel_hi:[1,0]
	v_pk_mul_f32 v[52:53], v[52:53], v[68:69] op_sel_hi:[1,0]
	v_pk_mul_f32 v[34:35], v[34:35], v[68:69] op_sel_hi:[1,0]
	v_pk_mul_f32 v[36:37], v[36:37], v[68:69] op_sel_hi:[1,0]
	v_pk_mul_f32 v[18:19], v[18:19], v[68:69] op_sel_hi:[1,0]
	v_pk_mul_f32 v[20:21], v[20:21], v[68:69] op_sel_hi:[1,0]
	v_pk_mul_f32 v[2:3], v[2:3], v[68:69] op_sel_hi:[1,0]
	v_pk_mul_f32 v[4:5], v[4:5], v[68:69] op_sel_hi:[1,0]
	v_cvt_pk_bf16_f32 v50, v50, v51
	v_cvt_pk_bf16_f32 v51, v52, v53
	v_cvt_pk_bf16_f32 v34, v34, v35
	v_cvt_pk_bf16_f32 v35, v36, v37
	v_cvt_pk_bf16_f32 v18, v18, v19
	v_cvt_pk_bf16_f32 v19, v20, v21
	v_cvt_pk_bf16_f32 v2, v2, v3
	v_cvt_pk_bf16_f32 v3, v4, v5
	global_store_dwordx2 v[66:67], v[50:51], off
	v_pk_mul_f32 v[50:51], v[54:55], v[68:69] op_sel_hi:[1,0]
	v_pk_mul_f32 v[52:53], v[56:57], v[68:69] op_sel_hi:[1,0]
	global_store_dwordx2 v[66:67], v[34:35], off offset:64
	v_pk_mul_f32 v[34:35], v[38:39], v[68:69] op_sel_hi:[1,0]
	v_pk_mul_f32 v[36:37], v[40:41], v[68:69] op_sel_hi:[1,0]
	global_store_dwordx2 v[66:67], v[18:19], off offset:128
	v_pk_mul_f32 v[18:19], v[22:23], v[68:69] op_sel_hi:[1,0]
	v_pk_mul_f32 v[20:21], v[24:25], v[68:69] op_sel_hi:[1,0]
	global_store_dwordx2 v[66:67], v[2:3], off offset:192
	v_pk_mul_f32 v[2:3], v[6:7], v[68:69] op_sel_hi:[1,0]
	v_pk_mul_f32 v[4:5], v[8:9], v[68:69] op_sel_hi:[1,0]
	v_cvt_pk_bf16_f32 v50, v50, v51
	v_cvt_pk_bf16_f32 v51, v52, v53
	v_cvt_pk_bf16_f32 v34, v34, v35
	v_cvt_pk_bf16_f32 v35, v36, v37
	v_cvt_pk_bf16_f32 v18, v18, v19
	v_cvt_pk_bf16_f32 v19, v20, v21
	v_cvt_pk_bf16_f32 v2, v2, v3
	v_cvt_pk_bf16_f32 v3, v4, v5
	global_store_dwordx2 v[66:67], v[50:51], off offset:16
	v_pk_mul_f32 v[50:51], v[58:59], v[68:69] op_sel_hi:[1,0]
	v_pk_mul_f32 v[52:53], v[60:61], v[68:69] op_sel_hi:[1,0]
	global_store_dwordx2 v[66:67], v[34:35], off offset:80
	v_pk_mul_f32 v[34:35], v[42:43], v[68:69] op_sel_hi:[1,0]
	v_pk_mul_f32 v[36:37], v[44:45], v[68:69] op_sel_hi:[1,0]
	global_store_dwordx2 v[66:67], v[18:19], off offset:144
	v_pk_mul_f32 v[18:19], v[26:27], v[68:69] op_sel_hi:[1,0]
	v_pk_mul_f32 v[20:21], v[28:29], v[68:69] op_sel_hi:[1,0]
	global_store_dwordx2 v[66:67], v[2:3], off offset:208
	v_pk_mul_f32 v[2:3], v[10:11], v[68:69] op_sel_hi:[1,0]
	v_pk_mul_f32 v[4:5], v[12:13], v[68:69] op_sel_hi:[1,0]
	v_cvt_pk_bf16_f32 v50, v50, v51
	v_cvt_pk_bf16_f32 v51, v52, v53
	v_cvt_pk_bf16_f32 v34, v34, v35
	v_cvt_pk_bf16_f32 v35, v36, v37
	v_cvt_pk_bf16_f32 v18, v18, v19
	v_cvt_pk_bf16_f32 v19, v20, v21
	v_cvt_pk_bf16_f32 v2, v2, v3
	v_cvt_pk_bf16_f32 v3, v4, v5
	global_store_dwordx2 v[66:67], v[50:51], off offset:32
	v_pk_mul_f32 v[50:51], v[62:63], v[68:69] op_sel_hi:[1,0]
	v_pk_mul_f32 v[52:53], v[64:65], v[68:69] op_sel_hi:[1,0]
	global_store_dwordx2 v[66:67], v[34:35], off offset:96
	v_pk_mul_f32 v[34:35], v[46:47], v[68:69] op_sel_hi:[1,0]
	v_pk_mul_f32 v[36:37], v[48:49], v[68:69] op_sel_hi:[1,0]
	global_store_dwordx2 v[66:67], v[18:19], off offset:160
	v_pk_mul_f32 v[18:19], v[30:31], v[68:69] op_sel_hi:[1,0]
	v_pk_mul_f32 v[20:21], v[32:33], v[68:69] op_sel_hi:[1,0]
	global_store_dwordx2 v[66:67], v[2:3], off offset:224
	v_pk_mul_f32 v[2:3], v[14:15], v[68:69] op_sel_hi:[1,0]
	v_pk_mul_f32 v[4:5], v[16:17], v[68:69] op_sel_hi:[1,0]
	s_add_i32 s19, s19, s36
	v_cvt_pk_bf16_f32 v50, v50, v51
	v_cvt_pk_bf16_f32 v51, v52, v53
	v_cvt_pk_bf16_f32 v34, v34, v35
	v_cvt_pk_bf16_f32 v35, v36, v37
	v_cvt_pk_bf16_f32 v18, v18, v19
	v_cvt_pk_bf16_f32 v19, v20, v21
	v_cvt_pk_bf16_f32 v2, v2, v3
	v_cvt_pk_bf16_f32 v3, v4, v5
	s_cmpk_gt_i32 s19, 0x1ff
	global_store_dwordx2 v[66:67], v[50:51], off offset:48
	global_store_dwordx2 v[66:67], v[34:35], off offset:112
	global_store_dwordx2 v[66:67], v[18:19], off offset:176
	global_store_dwordx2 v[66:67], v[2:3], off offset:240
	s_cbranch_scc1 .LBB0_101

.LBB0_101:
	s_setprio 0
	s_mov_b64 s[48:49], 0
